# stack1 + half of the teams (blockIdx bit 3) delayed ~7us at P5 start to de-phase P5/P6 epilogue load bursts
# baseline (speedup 1.0000x reference)
;     __host__ __device__ void init(int M_, int G_, int c_) { so.init(M_, 1024, G_, c_); }
;     __host__ __device__ void init(int M_, int G_, int c_) { so.init(M_, 3072, G_, c_); }
;     __host__ __device__ void init(int M_, int start_, int stride_, int limit_) { so.init(M_, 3072, stride_, start_); start = start_; stride = stride_; limit = limit_; }
; __device__ __forceinline__ unsigned long long rt() { return __builtin_amdgcn_s_memrealtime(); }
; __global__ void __launch_bounds__(NWAVES * 64, 2) fwd(Args args) {
;     ...
;     if (IN(5)) {
;         const unsigned long long amp_t0_5 = (PROBE_AMP == 5) ? rt() : 0ull;
;         _Pragma("unroll 1") for (int rep_ = 0; rep_ < ((PROBE == 5) ? 2 : 1); ++rep_) {
;         pg8::Gemm g{OAB, WBAB_T, M, D, 512, D, D, 1}; pg8::MergeOrder S; S.init(M, G, (int)blockIdx.x);
;         pg8::EpiMerge E{GAB, MRG};
;         pg8::gemm_phase<pg8::EpiMerge, pg8::MergeOrder, true, true>(lds + RING_OFF, g, S, E);
.LBB0_946:
	s_bfe_u32 s98, s2, 0x10003
	s_lshl_b32 s98, s98, 1
	s_cmp_eq_u32 s98, 0
	s_cbranch_scc1 .Lstag_done
